# padres2
# baseline (speedup 1.0000x reference)
.LBB0_395:
	s_nop 0
	s_nop 0
	s_andn2_b64 vcc, exec, s[0:1]
	s_cbranch_vccnz .LBB0_420
	s_cmp_eq_u32 s68, 3
	s_cselect_b64 s[0:1], -1, 0
	s_and_b64 s[22:23], s[0:1], exec
	v_readlane_b32 s76, v251, 13
	v_readlane_b32 s22, v254, 55
	v_readlane_b32 s9, v254, 56
	v_readlane_b32 s78, v251, 15
	v_readlane_b32 s79, v251, 16
	s_mul_i32 s6, s22, 3
	s_mul_i32 s9, s9, 27
	s_cselect_b32 s25, s79, 0
	s_cselect_b32 s24, s78, 0
	s_add_i32 s6, s6, s9
	s_add_i32 s26, s6, 2
	s_lshl_b64 s[38:39], s[26:27], 13
	v_readlane_b32 s40, v254, 57
	v_readlane_b32 s41, v254, 58
	s_add_u32 s14, s18, s40
	s_mul_i32 s9, s5, 0x1600000
	s_addc_u32 s17, s19, s41
	s_mul_hi_u32 s6, s5, 0x1600000
	s_add_u32 s9, s18, s9
	s_addc_u32 s6, s19, s6
	s_add_u32 s9, s9, 0xc000000
	s_addc_u32 s26, s6, 0
	s_cmp_eq_u32 s22, 1
	s_cselect_b64 s[22:23], -1, 0
	v_cndmask_b32_e64 v130, 0.5, 1.0, s[22:23]
	s_and_b64 s[22:23], s[22:23], exec
	s_cselect_b32 s44, s14, s9
	v_readlane_b32 s14, v254, 23
	s_mov_b32 s6, 0x1ea00000
	s_cselect_b32 s22, s6, 0x17c00000
	v_mov_b32_e32 v0, s14
	s_movk_i32 s6, 0x800
	s_waitcnt vmcnt(0)
	ds_read_b32 v2, v0
	s_cselect_b32 s6, s6, 0x1600
	s_cselect_b32 s45, s17, s26
	s_add_u32 s22, s18, s22
	s_addc_u32 s23, s19, 0
	s_add_u32 s9, s18, s38
	s_addc_u32 s14, s19, s39
	v_readlane_b32 s38, v254, 2
	s_add_u32 s62, s9, 0x100000
	v_mov_b32_e32 v0, v167
	s_waitcnt lgkmcnt(0)
	v_cmp_le_i32_e32 vcc, s38, v2
	s_addc_u32 s63, s14, 0
	s_lshr_b32 s64, s6, 6
	v_readfirstlane_b32 s9, v2
	s_and_b64 vcc, exec, vcc
	v_readfirstlane_b32 s14, v0
	v_readlane_b32 s77, v251, 14
	v_readlane_b32 s80, v251, 17
	v_readlane_b32 s81, v251, 18
	v_readlane_b32 s82, v251, 19
	v_readlane_b32 s83, v251, 20
	v_readlane_b32 s84, v251, 21
	v_readlane_b32 s85, v251, 22
	v_readlane_b32 s86, v251, 23
	v_readlane_b32 s87, v251, 24
	v_readlane_b32 s88, v251, 25
	v_readlane_b32 s89, v251, 26
	v_readlane_b32 s90, v251, 27
	v_readlane_b32 s91, v251, 28
	v_readlane_b32 s39, v254, 3
	s_cbranch_vccnz .LBB0_414
	v_lshlrev_b32_e32 v2, 4, v0
	v_add_u32_e32 v3, 0x2000, v2
	v_ashrrev_i32_e32 v4, 31, v3
	v_lshrrev_b32_e32 v4, 22, v4
	v_add_u32_e32 v4, v3, v4
	v_ashrrev_i32_e32 v4, 10, v4
	v_mul_i32_i24_e32 v5, 0x400, v4
	v_sub_u32_e32 v3, v3, v5
	v_lshrrev_b32_e32 v5, 4, v3
	v_bitop3_b32 v3, v5, v3, 32 bitop3:0x6c
	v_ashrrev_i32_e32 v5, 31, v3
	s_ashr_i32 s66, s9, 31
	v_lshrrev_b32_e32 v5, 26, v5
	s_lshr_b32 s39, s66, 29
	v_add_u32_e32 v5, v3, v5
	s_add_i32 s39, s9, s39
	s_ashr_i32 s38, s14, 6
	v_ashrrev_i32_e32 v6, 6, v5
	v_and_b32_e32 v5, 0xc0, v5
	s_ashr_i32 s40, s39, 3
	s_and_b32 s39, s39, -8
	s_ashr_i32 s41, s14, 8
	s_lshl_b32 s26, s6, 8
	s_lshl_b32 s17, s6, 9
	s_lshl_b32 s65, s38, 10
	v_sub_u32_e32 v3, v3, v5
	s_sub_i32 s39, s9, s39
	v_lshlrev_b32_e32 v7, 3, v4
	v_ashrrev_i16_sdwa v3, v217, sext(v3) dst_sel:DWORD dst_unused:UNUSED_PAD src0_sel:DWORD src1_sel:BYTE_0
	s_cmp_lt_i32 s39, 0
	v_readlane_b32 s29, v252, 33
	v_readlane_b32 s42, v252, 34
	v_and_b32_e32 v7, 0x7ffffff0, v7
	v_bfe_i32 v16, v3, 0, 16
	v_bfe_i32 v3, v0, 27, 1
	s_cselect_b32 s42, s42, s29
	v_add_u32_e32 v6, v6, v7
	v_lshlrev_b32_e32 v4, 5, v4
	v_lshrrev_b32_e32 v3, 22, v3
	s_mul_i32 s39, s39, s42
	v_mul_lo_u32 v14, v6, s6
	v_and_b32_e32 v15, 32, v4
	v_add_u32_e32 v3, v2, v3
	s_add_i32 s39, s39, s40
	v_or_b32_e32 v4, v14, v15
	v_and_b32_e32 v3, 0xfffffc00, v3
	s_ashr_i32 s40, s39, 31
	v_add_lshl_u32 v132, v4, v16, 1
	v_sub_u32_e32 v2, v2, v3
	v_ashrrev_i32_e32 v4, 31, v0
	s_lshr_b32 s40, s40, 26
	v_lshrrev_b32_e32 v3, 4, v2
	v_lshrrev_b32_e32 v4, 26, v4
	s_add_i32 s40, s39, s40
	v_bitop3_b32 v3, v3, v2, 32 bitop3:0x6c
	v_ashrrev_i32_e32 v2, 31, v2
	v_add_u32_e32 v4, v0, v4
	s_ashr_i32 s42, s40, 6
	v_lshrrev_b32_e32 v2, 26, v2
	v_ashrrev_i32_e32 v4, 6, v4
	s_lshl_b32 s46, s42, 3
	v_add_u32_e32 v2, v3, v2
	v_lshlrev_b32_e32 v5, 3, v4
	s_sub_i32 s42, s29, s46
	v_ashrrev_i32_e32 v2, 6, v2
	v_and_b32_e32 v5, 0x7ffffff0, v5
	s_min_i32 s47, s42, 8
	s_andn2_b32 s40, s40, 63
	v_add_u32_e32 v5, v2, v5
	v_mul_i32_i24_e32 v2, 64, v2
	s_sub_i32 s39, s39, s40
	s_sext_i32_i8 s40, s47
	v_sub_u32_e32 v2, v3, v2
	v_cvt_f32_i32_e32 v3, s40
	v_lshlrev_b32_e32 v4, 5, v4
	v_mul_lo_u32 v17, v5, s6
	v_and_b32_e32 v18, 32, v4
	v_ashrrev_i16_sdwa v2, v217, sext(v2) dst_sel:DWORD dst_unused:UNUSED_PAD src0_sel:DWORD src1_sel:BYTE_0
	v_or_b32_e32 v4, v17, v18
	v_bfe_i32 v19, v2, 0, 16
	v_add_lshl_u32 v134, v4, v19, 1
	v_cvt_f32_i32_e32 v2, s39
	v_rcp_iflag_f32_e32 v4, v3
	s_xor_b32 s42, s39, s40
	s_ashr_i32 s42, s42, 30
	s_or_b32 s48, s42, 1
	v_mul_f32_e32 v4, v2, v4
	v_trunc_f32_e32 v4, v4
	v_fma_f32 v2, -v4, v3, v2
	v_cvt_i32_f32_e32 v4, v4
	v_cmp_ge_f32_e64 s[42:43], |v2|, |v3|
	s_and_b64 s[42:43], s[42:43], exec
	s_cselect_b32 s40, s48, 0
	v_readfirstlane_b32 s42, v4
	s_add_i32 s40, s42, s40
	s_mul_i32 s42, s40, s47
	s_sub_i32 s39, s39, s42
	s_sext_i32_i8 s39, s39
	s_bfe_i64 s[42:43], s[40:41], 0x80000
	s_add_i32 s78, s46, s39
	s_mul_hi_i32 s43, s17, s42
	s_mul_i32 s42, s17, s42
	s_add_u32 s50, s44, s42
	s_addc_u32 s51, s45, s43
	s_add_i32 s67, s65, 0
	s_add_i32 m0, s67, 0x10000
	s_mul_i32 s46, s17, s78
	global_load_lds_dwordx4 v134, s[50:51]
	s_add_i32 m0, s67, 0x12000
	s_add_u32 s42, s50, s26
	global_load_lds_dwordx4 v132, s[50:51]
	s_addc_u32 s43, s51, 0
	s_add_i32 m0, s67, 0x14000
	s_mul_hi_i32 s39, s17, s78
	global_load_lds_dwordx4 v134, s[42:43]
	s_add_i32 m0, s67, 0x16000
	s_add_u32 s52, s22, s46
	v_mov_b32_e32 v135, v1
	v_mov_b32_e32 v133, v1
	s_addc_u32 s53, s23, s39
	s_add_i32 s68, s67, 0x2000
	v_lshl_add_u64 v[6:7], s[42:43], 0, v[134:135]
	v_lshl_add_u64 v[8:9], s[42:43], 0, v[132:133]
	global_load_lds_dwordx4 v132, s[42:43]
	s_mov_b32 m0, s67
	s_add_u32 s42, s52, s26
	global_load_lds_dwordx4 v134, s[52:53]
	s_mov_b32 m0, s68
	s_addc_u32 s43, s53, 0
	s_add_i32 s69, s67, 0x4000
	global_load_lds_dwordx4 v132, s[52:53]
	s_mov_b32 m0, s69
	s_add_i32 s70, s67, 0x6000
	global_load_lds_dwordx4 v134, s[42:43]
	s_mov_b32 m0, s70
	v_lshl_add_u64 v[2:3], s[50:51], 0, v[134:135]
	global_load_lds_dwordx4 v132, s[42:43]
	v_lshl_add_u64 v[4:5], s[50:51], 0, v[132:133]
	v_lshl_add_u64 v[10:11], s[52:53], 0, v[134:135]
	v_lshl_add_u64 v[12:13], s[52:53], 0, v[132:133]
	s_cmp_lg_u32 s41, 1
	s_cbranch_scc1 .LBB0_399
	s_barrier

.LBB0_411:
	s_nop 0
	s_nop 0
	s_nop 0
	s_nop 0
	s_nop 0
	s_nop 0
	s_nop 0
	s_nop 0
	s_nop 0
	s_nop 0
	s_nop 0
	s_nop 0
	s_nop 0
	s_nop 0
	s_nop 0
	s_nop 0
	s_nop 0
	s_nop 0
	s_nop 0
	s_nop 0
	s_nop 0
	s_nop 0
	s_nop 0
	s_nop 0
	s_nop 0
	s_nop 0
	s_nop 0
	s_nop 0
	s_nop 0
	s_nop 0
	s_nop 0
	s_nop 0
	s_nop 0
	s_nop 0
	s_nop 0
	s_nop 0
	s_nop 0
	s_nop 0
	s_nop 0
	s_nop 0
	s_nop 0
	s_nop 0
	s_nop 0
	s_nop 0
	s_nop 0
	s_nop 0
	s_nop 0
	s_nop 0
	s_nop 0
	s_nop 0
	s_nop 0
	s_nop 0
	s_nop 0
	s_nop 0
	s_nop 0
	s_nop 0
	s_nop 0
	s_nop 0
	s_nop 0
	s_nop 0
	s_nop 0
	s_nop 0
	s_waitcnt vmcnt(8)
	v_readlane_b32 s68, v254, 63
	s_cmpk_gt_u32 s14, 0xff
	v_readlane_b32 s69, v255, 0
	s_cbranch_scc1 .LBB0_413
	s_barrier
